# accumulator zeroing with 64-bit moves (half the VALU per tile) in 8 GEMM instances
# baseline (speedup 1.0000x reference)
; template <class Epi>
; __device__ __forceinline__ void gemm_phase(LAS unsigned char* lds, const Gemm g, const Epi& E) {
;     ...
;         const char* nA = has_next ? (const char*)g.A + (size_t)nxt.bz * g.strideA * 2 + (size_t)nxt.pm * tstepA : cA;
;         const char* nB = has_next ? (const char*)g.Bt + (size_t)nxt.bz * g.strideB * 2 + (size_t)nxt.pn * tstepB : cB;
;     ...
; #pragma unroll
;         for (int a = 0; a < 2; ++a)
; #pragma unroll
;             for (int b = 0; b < 2; ++b)
; #pragma unroll
;                 for (int m = 0; m < 4; ++m)
; #pragma unroll
;                     for (int n = 0; n < 2; ++n) acc[a][b][m][n] = (f32x4){0.f, 0.f, 0.f, 0.f};
.LBB0_68:
	s_ashr_i32 s21, s20, 31
	s_lshl_b64 s[36:37], s[20:21], 19
	s_add_u32 s54, s48, s36
	s_addc_u32 s55, s49, s37
	s_and_b64 s[36:37], s[42:43], exec
	s_cselect_b32 s11, s55, s87
	s_cselect_b32 s21, s54, s86
	s_ashr_i32 s23, s22, 31
	s_lshl_b64 s[36:37], s[22:23], 19
	s_add_u32 s76, s50, s36
	s_addc_u32 s77, s51, s37
	s_and_b64 s[36:37], s[42:43], exec
	s_cselect_b32 s23, s77, s39
	s_cselect_b32 s66, s76, s38
	s_add_u32 vcc_lo, s86, 0x40080
	s_addc_u32 vcc_hi, s87, 0
	s_add_u32 s36, s38, 0x100
	v_mov_b64_e32 v[0:1], 0
	v_mov_b64_e32 v[2:3], 0
	v_mov_b64_e32 v[4:5], 0
	v_mov_b64_e32 v[6:7], 0
	v_mov_b64_e32 v[8:9], 0
	v_mov_b64_e32 v[10:11], 0
	v_mov_b64_e32 v[12:13], 0
	v_mov_b64_e32 v[14:15], 0
	v_mov_b64_e32 v[16:17], 0
	v_mov_b64_e32 v[18:19], 0
	v_mov_b64_e32 v[20:21], 0
	v_mov_b64_e32 v[22:23], 0
	v_mov_b64_e32 v[24:25], 0
	v_mov_b64_e32 v[26:27], 0
	v_mov_b64_e32 v[28:29], 0
	v_mov_b64_e32 v[30:31], 0
	v_mov_b64_e32 v[32:33], 0
	v_mov_b64_e32 v[34:35], 0
	v_mov_b64_e32 v[36:37], 0
	v_mov_b64_e32 v[38:39], 0
	v_mov_b64_e32 v[40:41], 0
	v_mov_b64_e32 v[42:43], 0
	v_mov_b64_e32 v[44:45], 0
	v_mov_b64_e32 v[46:47], 0
	v_mov_b64_e32 v[48:49], 0
	v_mov_b64_e32 v[50:51], 0
	v_mov_b64_e32 v[52:53], 0
	v_mov_b64_e32 v[54:55], 0
	v_mov_b64_e32 v[56:57], 0
	v_mov_b64_e32 v[58:59], 0
	v_mov_b64_e32 v[60:61], 0
	v_mov_b64_e32 v[62:63], 0
	v_mov_b64_e32 v[64:65], 0
	v_mov_b64_e32 v[66:67], 0
	v_mov_b64_e32 v[68:69], 0
	v_mov_b64_e32 v[70:71], 0
	v_mov_b64_e32 v[72:73], 0
	v_mov_b64_e32 v[74:75], 0
	v_mov_b64_e32 v[76:77], 0
	v_mov_b64_e32 v[78:79], 0
	v_mov_b64_e32 v[80:81], 0
	v_mov_b64_e32 v[82:83], 0
	v_mov_b64_e32 v[84:85], 0
	v_mov_b64_e32 v[86:87], 0
	v_mov_b64_e32 v[88:89], 0
	v_mov_b64_e32 v[90:91], 0
	v_mov_b64_e32 v[92:93], 0
	v_mov_b64_e32 v[94:95], 0
	v_mov_b64_e32 v[96:97], 0
	v_mov_b64_e32 v[98:99], 0
	v_mov_b64_e32 v[100:101], 0
	v_mov_b64_e32 v[102:103], 0
	v_mov_b64_e32 v[104:105], 0
	v_mov_b64_e32 v[106:107], 0
	v_mov_b64_e32 v[108:109], 0
	v_mov_b64_e32 v[110:111], 0
	v_mov_b64_e32 v[112:113], 0
	v_mov_b64_e32 v[114:115], 0
	v_mov_b64_e32 v[116:117], 0
	v_mov_b64_e32 v[118:119], 0
	v_mov_b64_e32 v[120:121], 0
	v_mov_b64_e32 v[122:123], 0
	v_mov_b64_e32 v[124:125], 0
	v_mov_b64_e32 v[126:127], 0
	s_addc_u32 s37, s39, 0
	s_mov_b32 s84, -2
	s_waitcnt lgkmcnt(0)

; template <class Epi>
; __device__ __forceinline__ void gemm_phase(LAS unsigned char* lds, const Gemm g, const Epi& E) {
;     ...
; #pragma unroll
;         for (int a = 0; a < 2; ++a)
; #pragma unroll
;             for (int b = 0; b < 2; ++b)
; #pragma unroll
;                 for (int m = 0; m < 4; ++m)
; #pragma unroll
;                     for (int n = 0; n < 2; ++n) acc[a][b][m][n] = (f32x4){0.f, 0.f, 0.f, 0.f};
.LBB0_141:
	s_add_u32 s13, s22, 0x100
	v_mov_b64_e32 v[0:1], 0
	v_mov_b64_e32 v[2:3], 0
	v_mov_b64_e32 v[4:5], 0
	v_mov_b64_e32 v[6:7], 0
	v_mov_b64_e32 v[8:9], 0
	v_mov_b64_e32 v[10:11], 0
	v_mov_b64_e32 v[12:13], 0
	v_mov_b64_e32 v[14:15], 0
	v_mov_b64_e32 v[16:17], 0
	v_mov_b64_e32 v[18:19], 0
	v_mov_b64_e32 v[20:21], 0
	v_mov_b64_e32 v[22:23], 0
	v_mov_b64_e32 v[24:25], 0
	v_mov_b64_e32 v[26:27], 0
	v_mov_b64_e32 v[28:29], 0
	v_mov_b64_e32 v[30:31], 0
	v_mov_b64_e32 v[32:33], 0
	v_mov_b64_e32 v[34:35], 0
	v_mov_b64_e32 v[36:37], 0
	v_mov_b64_e32 v[38:39], 0
	v_mov_b64_e32 v[40:41], 0
	v_mov_b64_e32 v[42:43], 0
	v_mov_b64_e32 v[44:45], 0
	v_mov_b64_e32 v[46:47], 0
	v_mov_b64_e32 v[48:49], 0
	v_mov_b64_e32 v[50:51], 0
	v_mov_b64_e32 v[52:53], 0
	v_mov_b64_e32 v[54:55], 0
	v_mov_b64_e32 v[56:57], 0
	v_mov_b64_e32 v[58:59], 0
	v_mov_b64_e32 v[60:61], 0
	v_mov_b64_e32 v[62:63], 0
	v_mov_b64_e32 v[64:65], 0
	v_mov_b64_e32 v[66:67], 0
	v_mov_b64_e32 v[68:69], 0
	v_mov_b64_e32 v[70:71], 0
	v_mov_b64_e32 v[72:73], 0
	v_mov_b64_e32 v[74:75], 0
	v_mov_b64_e32 v[76:77], 0
	v_mov_b64_e32 v[78:79], 0
	v_mov_b64_e32 v[80:81], 0
	v_mov_b64_e32 v[82:83], 0
	v_mov_b64_e32 v[84:85], 0
	v_mov_b64_e32 v[86:87], 0
	v_mov_b64_e32 v[88:89], 0
	v_mov_b64_e32 v[90:91], 0
	v_mov_b64_e32 v[92:93], 0
	v_mov_b64_e32 v[94:95], 0
	v_mov_b64_e32 v[96:97], 0
	v_mov_b64_e32 v[98:99], 0
	v_mov_b64_e32 v[100:101], 0
	v_mov_b64_e32 v[102:103], 0
	v_mov_b64_e32 v[104:105], 0
	v_mov_b64_e32 v[106:107], 0
	v_mov_b64_e32 v[108:109], 0
	v_mov_b64_e32 v[110:111], 0
	v_mov_b64_e32 v[112:113], 0
	v_mov_b64_e32 v[114:115], 0
	v_mov_b64_e32 v[116:117], 0
	v_mov_b64_e32 v[118:119], 0
	v_mov_b64_e32 v[120:121], 0
	v_mov_b64_e32 v[122:123], 0
	v_mov_b64_e32 v[124:125], 0
	v_mov_b64_e32 v[126:127], 0
	s_addc_u32 s30, s23, 0
	s_mov_b32 s31, -2

; template <class Epi>
; __device__ __forceinline__ void gemm_phase(LAS unsigned char* lds, const Gemm g, const Epi& E) {
;     ...
;         const char* nA = has_next ? (const char*)g.A + (size_t)nxt.bz * g.strideA * 2 + (size_t)nxt.pm * tstepA : cA;
;         const char* nB = has_next ? (const char*)g.Bt + (size_t)nxt.bz * g.strideB * 2 + (size_t)nxt.pn * tstepB : cB;
;     ...
; #pragma unroll
;         for (int a = 0; a < 2; ++a)
; #pragma unroll
;             for (int b = 0; b < 2; ++b)
; #pragma unroll
;                 for (int m = 0; m < 4; ++m)
; #pragma unroll
;                     for (int n = 0; n < 2; ++n) acc[a][b][m][n] = (f32x4){0.f, 0.f, 0.f, 0.f};
.LBB0_194:
	s_lshl_b64 s[54:55], s[38:39], 19
	s_add_u32 s56, s58, s54
	s_addc_u32 s57, s59, s55
	s_and_b64 s[42:43], s[42:43], exec
	s_cselect_b32 s23, s57, s83
	s_cselect_b32 s39, s56, s82
	s_add_u32 s82, s82, 0x100
	v_mov_b64_e32 v[0:1], 0
	v_mov_b64_e32 v[2:3], 0
	v_mov_b64_e32 v[4:5], 0
	v_mov_b64_e32 v[6:7], 0
	v_mov_b64_e32 v[8:9], 0
	v_mov_b64_e32 v[10:11], 0
	v_mov_b64_e32 v[12:13], 0
	v_mov_b64_e32 v[14:15], 0
	v_mov_b64_e32 v[16:17], 0
	v_mov_b64_e32 v[18:19], 0
	v_mov_b64_e32 v[20:21], 0
	v_mov_b64_e32 v[22:23], 0
	v_mov_b64_e32 v[24:25], 0
	v_mov_b64_e32 v[26:27], 0
	v_mov_b64_e32 v[28:29], 0
	v_mov_b64_e32 v[30:31], 0
	v_mov_b64_e32 v[32:33], 0
	v_mov_b64_e32 v[34:35], 0
	v_mov_b64_e32 v[36:37], 0
	v_mov_b64_e32 v[38:39], 0
	v_mov_b64_e32 v[40:41], 0
	v_mov_b64_e32 v[42:43], 0
	v_mov_b64_e32 v[44:45], 0
	v_mov_b64_e32 v[46:47], 0
	v_mov_b64_e32 v[48:49], 0
	v_mov_b64_e32 v[50:51], 0
	v_mov_b64_e32 v[52:53], 0
	v_mov_b64_e32 v[54:55], 0
	v_mov_b64_e32 v[56:57], 0
	v_mov_b64_e32 v[58:59], 0
	v_mov_b64_e32 v[60:61], 0
	v_mov_b64_e32 v[62:63], 0
	v_mov_b64_e32 v[64:65], 0
	v_mov_b64_e32 v[66:67], 0
	v_mov_b64_e32 v[68:69], 0
	v_mov_b64_e32 v[70:71], 0
	v_mov_b64_e32 v[72:73], 0
	v_mov_b64_e32 v[74:75], 0
	v_mov_b64_e32 v[76:77], 0
	v_mov_b64_e32 v[78:79], 0
	v_mov_b64_e32 v[80:81], 0
	v_mov_b64_e32 v[82:83], 0
	v_mov_b64_e32 v[84:85], 0
	v_mov_b64_e32 v[86:87], 0
	v_mov_b64_e32 v[88:89], 0
	v_mov_b64_e32 v[90:91], 0
	v_mov_b64_e32 v[92:93], 0
	v_mov_b64_e32 v[94:95], 0
	v_mov_b64_e32 v[96:97], 0
	v_mov_b64_e32 v[98:99], 0
	v_mov_b64_e32 v[100:101], 0
	v_mov_b64_e32 v[102:103], 0
	v_mov_b64_e32 v[104:105], 0
	v_mov_b64_e32 v[106:107], 0
	v_mov_b64_e32 v[108:109], 0
	v_mov_b64_e32 v[110:111], 0
	v_mov_b64_e32 v[112:113], 0
	v_mov_b64_e32 v[114:115], 0
	v_mov_b64_e32 v[116:117], 0
	v_mov_b64_e32 v[118:119], 0
	v_mov_b64_e32 v[120:121], 0
	v_mov_b64_e32 v[122:123], 0
	v_mov_b64_e32 v[124:125], 0
	v_mov_b64_e32 v[126:127], 0
	s_addc_u32 s83, s83, 0
	s_mov_b32 s84, -2

; template <class Epi>
; __device__ __forceinline__ void gemm_phase(LAS unsigned char* lds, const Gemm g, const Epi& E) {
;     ...
;         const char* nA = has_next ? (const char*)g.A + (size_t)nxt.bz * g.strideA * 2 + (size_t)nxt.pm * tstepA : cA;
;         const char* nB = has_next ? (const char*)g.Bt + (size_t)nxt.bz * g.strideB * 2 + (size_t)nxt.pn * tstepB : cB;
;     ...
; #pragma unroll
;         for (int a = 0; a < 2; ++a)
; #pragma unroll
;             for (int b = 0; b < 2; ++b)
; #pragma unroll
;                 for (int m = 0; m < 4; ++m)
; #pragma unroll
;                     for (int n = 0; n < 2; ++n) acc[a][b][m][n] = (f32x4){0.f, 0.f, 0.f, 0.f};
.LBB0_370:
	s_ashr_i32 s39, s38, 31
	s_lshl_b64 s[48:49], s[38:39], 19
	s_add_u32 s48, s8, s48
	s_addc_u32 s49, s9, s49
	s_and_b64 s[54:55], s[40:41], exec
	s_cselect_b32 s39, s49, s21
	s_cselect_b32 s43, s48, s20
	s_ashr_i32 s47, s46, 31
	s_lshl_b64 s[54:55], s[46:47], 19
	s_add_u32 s56, s6, s54
	s_addc_u32 s57, s7, s55
	s_and_b64 s[54:55], s[40:41], exec
	s_cselect_b32 s45, s57, s23
	s_cselect_b32 s47, s56, s22
	s_add_u32 s20, s20, 0x40080
	s_addc_u32 s21, s21, 0
	s_add_u32 s77, s22, 0x100
	v_mov_b64_e32 v[0:1], 0
	v_mov_b64_e32 v[2:3], 0
	v_mov_b64_e32 v[4:5], 0
	v_mov_b64_e32 v[6:7], 0
	v_mov_b64_e32 v[8:9], 0
	v_mov_b64_e32 v[10:11], 0
	v_mov_b64_e32 v[12:13], 0
	v_mov_b64_e32 v[14:15], 0
	v_mov_b64_e32 v[16:17], 0
	v_mov_b64_e32 v[18:19], 0
	v_mov_b64_e32 v[20:21], 0
	v_mov_b64_e32 v[22:23], 0
	v_mov_b64_e32 v[24:25], 0
	v_mov_b64_e32 v[26:27], 0
	v_mov_b64_e32 v[28:29], 0
	v_mov_b64_e32 v[30:31], 0
	v_mov_b64_e32 v[32:33], 0
	v_mov_b64_e32 v[34:35], 0
	v_mov_b64_e32 v[36:37], 0
	v_mov_b64_e32 v[38:39], 0
	v_mov_b64_e32 v[40:41], 0
	v_mov_b64_e32 v[42:43], 0
	v_mov_b64_e32 v[44:45], 0
	v_mov_b64_e32 v[46:47], 0
	v_mov_b64_e32 v[48:49], 0
	v_mov_b64_e32 v[50:51], 0
	v_mov_b64_e32 v[52:53], 0
	v_mov_b64_e32 v[54:55], 0
	v_mov_b64_e32 v[56:57], 0
	v_mov_b64_e32 v[58:59], 0
	v_mov_b64_e32 v[60:61], 0
	v_mov_b64_e32 v[62:63], 0
	v_mov_b64_e32 v[64:65], 0
	v_mov_b64_e32 v[66:67], 0
	v_mov_b64_e32 v[68:69], 0
	v_mov_b64_e32 v[70:71], 0
	v_mov_b64_e32 v[72:73], 0
	v_mov_b64_e32 v[74:75], 0
	v_mov_b64_e32 v[76:77], 0
	v_mov_b64_e32 v[78:79], 0
	v_mov_b64_e32 v[80:81], 0
	v_mov_b64_e32 v[82:83], 0
	v_mov_b64_e32 v[84:85], 0
	v_mov_b64_e32 v[86:87], 0
	v_mov_b64_e32 v[88:89], 0
	v_mov_b64_e32 v[90:91], 0
	v_mov_b64_e32 v[92:93], 0
	v_mov_b64_e32 v[94:95], 0
	v_mov_b64_e32 v[96:97], 0
	v_mov_b64_e32 v[98:99], 0
	v_mov_b64_e32 v[100:101], 0
	v_mov_b64_e32 v[102:103], 0
	v_mov_b64_e32 v[104:105], 0
	v_mov_b64_e32 v[106:107], 0
	v_mov_b64_e32 v[108:109], 0
	v_mov_b64_e32 v[110:111], 0
	v_mov_b64_e32 v[112:113], 0
	v_mov_b64_e32 v[114:115], 0
	v_mov_b64_e32 v[116:117], 0
	v_mov_b64_e32 v[118:119], 0
	v_mov_b64_e32 v[120:121], 0
	v_mov_b64_e32 v[122:123], 0
	v_mov_b64_e32 v[124:125], 0
	v_mov_b64_e32 v[126:127], 0
	s_addc_u32 s82, s23, 0
	s_mov_b32 s83, -2

; template <class Epi>
; __device__ __forceinline__ void gemm_phase(LAS unsigned char* lds, const Gemm g, const Epi& E) {
;     ...
; #pragma unroll
;         for (int a = 0; a < 2; ++a)
; #pragma unroll
;             for (int b = 0; b < 2; ++b)
; #pragma unroll
;                 for (int m = 0; m < 4; ++m)
; #pragma unroll
;                     for (int n = 0; n < 2; ++n) acc[a][b][m][n] = (f32x4){0.f, 0.f, 0.f, 0.f};
.LBB0_500:
	s_add_u32 s76, s22, 0x100
	v_mov_b64_e32 v[0:1], 0
	v_mov_b64_e32 v[2:3], 0
	v_mov_b64_e32 v[4:5], 0
	v_mov_b64_e32 v[6:7], 0
	v_mov_b64_e32 v[8:9], 0
	v_mov_b64_e32 v[10:11], 0
	v_mov_b64_e32 v[12:13], 0
	v_mov_b64_e32 v[14:15], 0
	v_mov_b64_e32 v[16:17], 0
	v_mov_b64_e32 v[18:19], 0
	v_mov_b64_e32 v[20:21], 0
	v_mov_b64_e32 v[22:23], 0
	v_mov_b64_e32 v[24:25], 0
	v_mov_b64_e32 v[26:27], 0
	v_mov_b64_e32 v[28:29], 0
	v_mov_b64_e32 v[30:31], 0
	v_mov_b64_e32 v[32:33], 0
	v_mov_b64_e32 v[34:35], 0
	v_mov_b64_e32 v[36:37], 0
	v_mov_b64_e32 v[38:39], 0
	v_mov_b64_e32 v[40:41], 0
	v_mov_b64_e32 v[42:43], 0
	v_mov_b64_e32 v[44:45], 0
	v_mov_b64_e32 v[46:47], 0
	v_mov_b64_e32 v[48:49], 0
	v_mov_b64_e32 v[50:51], 0
	v_mov_b64_e32 v[52:53], 0
	v_mov_b64_e32 v[54:55], 0
	v_mov_b64_e32 v[56:57], 0
	v_mov_b64_e32 v[58:59], 0
	v_mov_b64_e32 v[60:61], 0
	v_mov_b64_e32 v[62:63], 0
	v_mov_b64_e32 v[64:65], 0
	v_mov_b64_e32 v[66:67], 0
	v_mov_b64_e32 v[68:69], 0
	v_mov_b64_e32 v[70:71], 0
	v_mov_b64_e32 v[72:73], 0
	v_mov_b64_e32 v[74:75], 0
	v_mov_b64_e32 v[76:77], 0
	v_mov_b64_e32 v[78:79], 0
	v_mov_b64_e32 v[80:81], 0
	v_mov_b64_e32 v[82:83], 0
	v_mov_b64_e32 v[84:85], 0
	v_mov_b64_e32 v[86:87], 0
	v_mov_b64_e32 v[88:89], 0
	v_mov_b64_e32 v[90:91], 0
	v_mov_b64_e32 v[92:93], 0
	v_mov_b64_e32 v[94:95], 0
	v_mov_b64_e32 v[96:97], 0
	v_mov_b64_e32 v[98:99], 0
	v_mov_b64_e32 v[100:101], 0
	v_mov_b64_e32 v[102:103], 0
	v_mov_b64_e32 v[104:105], 0
	v_mov_b64_e32 v[106:107], 0
	v_mov_b64_e32 v[108:109], 0
	v_mov_b64_e32 v[110:111], 0
	v_mov_b64_e32 v[112:113], 0
	v_mov_b64_e32 v[114:115], 0
	v_mov_b64_e32 v[116:117], 0
	v_mov_b64_e32 v[118:119], 0
	v_mov_b64_e32 v[120:121], 0
	v_mov_b64_e32 v[122:123], 0
	v_mov_b64_e32 v[124:125], 0
	v_mov_b64_e32 v[126:127], 0
	s_addc_u32 s77, s23, 0
	s_mov_b32 s82, -2
	s_waitcnt lgkmcnt(0)
	v_add_u32_e32 v182, 0x10000, v167

; template <class Epi>
; __device__ __forceinline__ void gemm_phase(LAS unsigned char* lds, const Gemm g, const Epi& E) {
;     ...
; #pragma unroll
;         for (int a = 0; a < 2; ++a)
; #pragma unroll
;             for (int b = 0; b < 2; ++b)
; #pragma unroll
;                 for (int m = 0; m < 4; ++m)
; #pragma unroll
;                     for (int n = 0; n < 2; ++n) acc[a][b][m][n] = (f32x4){0.f, 0.f, 0.f, 0.f};
.LBB0_546:
	s_add_u32 s12, s22, 0x100
	v_mov_b64_e32 v[0:1], 0
	v_mov_b64_e32 v[2:3], 0
	v_mov_b64_e32 v[4:5], 0
	v_mov_b64_e32 v[6:7], 0
	v_mov_b64_e32 v[8:9], 0
	v_mov_b64_e32 v[10:11], 0
	v_mov_b64_e32 v[12:13], 0
	v_mov_b64_e32 v[14:15], 0
	v_mov_b64_e32 v[16:17], 0
	v_mov_b64_e32 v[18:19], 0
	v_mov_b64_e32 v[20:21], 0
	v_mov_b64_e32 v[22:23], 0
	v_mov_b64_e32 v[24:25], 0
	v_mov_b64_e32 v[26:27], 0
	v_mov_b64_e32 v[28:29], 0
	v_mov_b64_e32 v[30:31], 0
	v_mov_b64_e32 v[32:33], 0
	v_mov_b64_e32 v[34:35], 0
	v_mov_b64_e32 v[36:37], 0
	v_mov_b64_e32 v[38:39], 0
	v_mov_b64_e32 v[40:41], 0
	v_mov_b64_e32 v[42:43], 0
	v_mov_b64_e32 v[44:45], 0
	v_mov_b64_e32 v[46:47], 0
	v_mov_b64_e32 v[48:49], 0
	v_mov_b64_e32 v[50:51], 0
	v_mov_b64_e32 v[52:53], 0
	v_mov_b64_e32 v[54:55], 0
	v_mov_b64_e32 v[56:57], 0
	v_mov_b64_e32 v[58:59], 0
	v_mov_b64_e32 v[60:61], 0
	v_mov_b64_e32 v[62:63], 0
	v_mov_b64_e32 v[64:65], 0
	v_mov_b64_e32 v[66:67], 0
	v_mov_b64_e32 v[68:69], 0
	v_mov_b64_e32 v[70:71], 0
	v_mov_b64_e32 v[72:73], 0
	v_mov_b64_e32 v[74:75], 0
	v_mov_b64_e32 v[76:77], 0
	v_mov_b64_e32 v[78:79], 0
	v_mov_b64_e32 v[80:81], 0
	v_mov_b64_e32 v[82:83], 0
	v_mov_b64_e32 v[84:85], 0
	v_mov_b64_e32 v[86:87], 0
	v_mov_b64_e32 v[88:89], 0
	v_mov_b64_e32 v[90:91], 0
	v_mov_b64_e32 v[92:93], 0
	v_mov_b64_e32 v[94:95], 0
	v_mov_b64_e32 v[96:97], 0
	v_mov_b64_e32 v[98:99], 0
	v_mov_b64_e32 v[100:101], 0
	v_mov_b64_e32 v[102:103], 0
	v_mov_b64_e32 v[104:105], 0
	v_mov_b64_e32 v[106:107], 0
	v_mov_b64_e32 v[108:109], 0
	v_mov_b64_e32 v[110:111], 0
	v_mov_b64_e32 v[112:113], 0
	v_mov_b64_e32 v[114:115], 0
	v_mov_b64_e32 v[116:117], 0
	v_mov_b64_e32 v[118:119], 0
	v_mov_b64_e32 v[120:121], 0
	v_mov_b64_e32 v[122:123], 0
	v_mov_b64_e32 v[124:125], 0
	v_mov_b64_e32 v[126:127], 0
	s_addc_u32 s13, s23, 0
	s_mov_b32 s42, -2
	v_add_u32_e32 v186, 0x10000, v149

; template <class Epi>
; __device__ __forceinline__ void gemm_phase(LAS unsigned char* lds, const Gemm g, const Epi& E) {
;     ...
;         const char* nA = has_next ? (const char*)g.A + (size_t)nxt.bz * g.strideA * 2 + (size_t)nxt.pm * tstepA : cA;
;         const char* nB = has_next ? (const char*)g.Bt + (size_t)nxt.bz * g.strideB * 2 + (size_t)nxt.pn * tstepB : cB;
;     ...
; #pragma unroll
;         for (int a = 0; a < 2; ++a)
; #pragma unroll
;             for (int b = 0; b < 2; ++b)
; #pragma unroll
;                 for (int m = 0; m < 4; ++m)
; #pragma unroll
;                     for (int n = 0; n < 2; ++n) acc[a][b][m][n] = (f32x4){0.f, 0.f, 0.f, 0.f};
.LBB0_607:
	s_ashr_i32 s21, s20, 31
	s_lshl_b64 s[26:27], s[20:21], 19
	s_add_u32 s26, s8, s26
	s_addc_u32 s27, s9, s27
	s_and_b64 s[28:29], s[40:41], exec
	s_cselect_b32 s21, s27, s37
	s_cselect_b32 s31, s26, s36
	s_ashr_i32 s23, s22, 31
	s_lshl_b64 s[28:29], s[22:23], 19
	s_add_u32 s28, s10, s28
	s_addc_u32 s29, s11, s29
	s_and_b64 s[42:43], s[40:41], exec
	s_cselect_b32 s23, s29, s39
	s_cselect_b32 s66, s28, s38
	s_add_u32 s36, s36, 0x40080
	s_addc_u32 s37, s37, 0
	s_add_u32 s68, s38, 0x100
	v_mov_b64_e32 v[0:1], 0
	v_mov_b64_e32 v[2:3], 0
	v_mov_b64_e32 v[4:5], 0
	v_mov_b64_e32 v[6:7], 0
	v_mov_b64_e32 v[8:9], 0
	v_mov_b64_e32 v[10:11], 0
	v_mov_b64_e32 v[12:13], 0
	v_mov_b64_e32 v[14:15], 0
	v_mov_b64_e32 v[16:17], 0
	v_mov_b64_e32 v[18:19], 0
	v_mov_b64_e32 v[20:21], 0
	v_mov_b64_e32 v[22:23], 0
	v_mov_b64_e32 v[24:25], 0
	v_mov_b64_e32 v[26:27], 0
	v_mov_b64_e32 v[28:29], 0
	v_mov_b64_e32 v[30:31], 0
	v_mov_b64_e32 v[32:33], 0
	v_mov_b64_e32 v[34:35], 0
	v_mov_b64_e32 v[36:37], 0
	v_mov_b64_e32 v[38:39], 0
	v_mov_b64_e32 v[40:41], 0
	v_mov_b64_e32 v[42:43], 0
	v_mov_b64_e32 v[44:45], 0
	v_mov_b64_e32 v[46:47], 0
	v_mov_b64_e32 v[48:49], 0
	v_mov_b64_e32 v[50:51], 0
	v_mov_b64_e32 v[52:53], 0
	v_mov_b64_e32 v[54:55], 0
	v_mov_b64_e32 v[56:57], 0
	v_mov_b64_e32 v[58:59], 0
	v_mov_b64_e32 v[60:61], 0
	v_mov_b64_e32 v[62:63], 0
	v_mov_b64_e32 v[64:65], 0
	v_mov_b64_e32 v[66:67], 0
	v_mov_b64_e32 v[68:69], 0
	v_mov_b64_e32 v[70:71], 0
	v_mov_b64_e32 v[72:73], 0
	v_mov_b64_e32 v[74:75], 0
	v_mov_b64_e32 v[76:77], 0
	v_mov_b64_e32 v[78:79], 0
	v_mov_b64_e32 v[80:81], 0
	v_mov_b64_e32 v[82:83], 0
	v_mov_b64_e32 v[84:85], 0
	v_mov_b64_e32 v[86:87], 0
	v_mov_b64_e32 v[88:89], 0
	v_mov_b64_e32 v[90:91], 0
	v_mov_b64_e32 v[92:93], 0
	v_mov_b64_e32 v[94:95], 0
	v_mov_b64_e32 v[96:97], 0
	v_mov_b64_e32 v[98:99], 0
	v_mov_b64_e32 v[100:101], 0
	v_mov_b64_e32 v[102:103], 0
	v_mov_b64_e32 v[104:105], 0
	v_mov_b64_e32 v[106:107], 0
	v_mov_b64_e32 v[108:109], 0
	v_mov_b64_e32 v[110:111], 0
	v_mov_b64_e32 v[112:113], 0
	v_mov_b64_e32 v[114:115], 0
	v_mov_b64_e32 v[116:117], 0
	v_mov_b64_e32 v[118:119], 0
	v_mov_b64_e32 v[120:121], 0
	v_mov_b64_e32 v[122:123], 0
	v_mov_b64_e32 v[124:125], 0
	v_mov_b64_e32 v[126:127], 0
	s_addc_u32 s69, s39, 0
	s_mov_b32 s76, -2
	v_add_u32_e32 v149, 0x10000, v145

; template <class Epi>
; __device__ __forceinline__ void gemm_phase(LAS unsigned char* lds, const Gemm g, const Epi& E) {
;     ...
;         const char* nA = has_next ? (const char*)g.A + (size_t)nxt.bz * g.strideA * 2 + (size_t)nxt.pm * tstepA : cA;
;         const char* nB = has_next ? (const char*)g.Bt + (size_t)nxt.bz * g.strideB * 2 + (size_t)nxt.pn * tstepB : cB;
;     ...
; #pragma unroll
;         for (int a = 0; a < 2; ++a)
; #pragma unroll
;             for (int b = 0; b < 2; ++b)
; #pragma unroll
;                 for (int m = 0; m < 4; ++m)
; #pragma unroll
;                     for (int n = 0; n < 2; ++n) acc[a][b][m][n] = (f32x4){0.f, 0.f, 0.f, 0.f};
.LBB0_991:
	s_ashr_i32 s47, s46, 31
	s_lshl_b64 s[24:25], s[46:47], 19
	s_add_u32 s56, s30, s24
	s_addc_u32 s57, s31, s25
	s_and_b64 s[24:25], s[40:41], exec
	s_cselect_b32 s43, s57, s21
	s_cselect_b32 s45, s56, s20
	s_ashr_i32 s49, s48, 31
	s_lshl_b64 s[24:25], s[48:49], 19
	s_add_u32 s68, s90, s24
	s_addc_u32 s69, s91, s25
	s_and_b64 s[24:25], s[40:41], exec
	s_cselect_b32 s47, s69, s23
	s_cselect_b32 s49, s68, s22
	s_add_u32 s20, s20, 0x40080
	s_addc_u32 s21, s21, 0
	s_add_u32 s82, s22, 0x100
	v_mov_b64_e32 v[0:1], 0
	v_mov_b64_e32 v[2:3], 0
	v_mov_b64_e32 v[4:5], 0
	v_mov_b64_e32 v[6:7], 0
	v_mov_b64_e32 v[8:9], 0
	v_mov_b64_e32 v[10:11], 0
	v_mov_b64_e32 v[12:13], 0
	v_mov_b64_e32 v[14:15], 0
	v_mov_b64_e32 v[16:17], 0
	v_mov_b64_e32 v[18:19], 0
	v_mov_b64_e32 v[20:21], 0
	v_mov_b64_e32 v[22:23], 0
	v_mov_b64_e32 v[24:25], 0
	v_mov_b64_e32 v[26:27], 0
	v_mov_b64_e32 v[28:29], 0
	v_mov_b64_e32 v[30:31], 0
	v_mov_b64_e32 v[32:33], 0
	v_mov_b64_e32 v[34:35], 0
	v_mov_b64_e32 v[36:37], 0
	v_mov_b64_e32 v[38:39], 0
	v_mov_b64_e32 v[40:41], 0
	v_mov_b64_e32 v[42:43], 0
	v_mov_b64_e32 v[44:45], 0
	v_mov_b64_e32 v[46:47], 0
	v_mov_b64_e32 v[48:49], 0
	v_mov_b64_e32 v[50:51], 0
	v_mov_b64_e32 v[52:53], 0
	v_mov_b64_e32 v[54:55], 0
	v_mov_b64_e32 v[56:57], 0
	v_mov_b64_e32 v[58:59], 0
	v_mov_b64_e32 v[60:61], 0
	v_mov_b64_e32 v[62:63], 0
	v_mov_b64_e32 v[64:65], 0
	v_mov_b64_e32 v[66:67], 0
	v_mov_b64_e32 v[68:69], 0
	v_mov_b64_e32 v[70:71], 0
	v_mov_b64_e32 v[72:73], 0
	v_mov_b64_e32 v[74:75], 0
	v_mov_b64_e32 v[76:77], 0
	v_mov_b64_e32 v[78:79], 0
	v_mov_b64_e32 v[80:81], 0
	v_mov_b64_e32 v[82:83], 0
	v_mov_b64_e32 v[84:85], 0
	v_mov_b64_e32 v[86:87], 0
	v_mov_b64_e32 v[88:89], 0
	v_mov_b64_e32 v[90:91], 0
	v_mov_b64_e32 v[92:93], 0
	v_mov_b64_e32 v[94:95], 0
	v_mov_b64_e32 v[96:97], 0
	v_mov_b64_e32 v[98:99], 0
	v_mov_b64_e32 v[100:101], 0
	v_mov_b64_e32 v[102:103], 0
	v_mov_b64_e32 v[104:105], 0
	v_mov_b64_e32 v[106:107], 0
	v_mov_b64_e32 v[108:109], 0
	v_mov_b64_e32 v[110:111], 0
	v_mov_b64_e32 v[112:113], 0
	v_mov_b64_e32 v[114:115], 0
	v_mov_b64_e32 v[116:117], 0
	v_mov_b64_e32 v[118:119], 0
	v_mov_b64_e32 v[120:121], 0
	v_mov_b64_e32 v[122:123], 0
	v_mov_b64_e32 v[124:125], 0
	v_mov_b64_e32 v[126:127], 0
	s_addc_u32 s83, s23, 0
	s_mov_b32 s84, -2
	v_add_u32_e32 v186, 0x10000, v160
